# rw_lora: bf16 results stored straight from the MFMA accumulator layout as 8-byte stores (12 per wave and item); LDS transpose, readback and 48 two-byte stores removed
# speedup vs baseline: 1.0001x; 1.0001x over previous
.LBB0_944:
	s_lshl_b32 s18, s48, 4
	s_mov_b32 s10, 0xffffde00
	s_mov_b32 s11, -1
	s_mov_b32 s20, 0x2200
	s_mov_b32 s21, 0
	global_load_dword v50, v[2:3], off
	global_load_dword v51, v[4:5], off
	global_load_dword v52, v[6:7], off
	global_load_dword v53, v[8:9], off
	v_or_b32_e32 v20, s18, v220
	v_mad_i64_i32 v[22:23], s[0:1], v20, s23, v[14:15]
	v_lshl_add_u64 v[22:23], v[22:23], 0, s[16:17]
	v_lshl_add_u64 v[26:27], v[22:23], 0, v[0:1]
	v_lshl_add_u64 v[34:35], v[26:27], 0, s[10:11]
	v_lshl_add_u64 v[36:37], v[26:27], 0, s[20:21]
	global_load_ushort v38, v[26:27], off
	global_load_ushort v42, v[34:35], off
	global_load_ushort v46, v[36:37], off
	v_lshl_add_u64 v[28:29], v[22:23], 0, v[18:19]
	v_lshl_add_u64 v[34:35], v[28:29], 0, s[10:11]
	v_lshl_add_u64 v[36:37], v[28:29], 0, s[20:21]
	global_load_ushort v39, v[28:29], off
	global_load_ushort v43, v[34:35], off
	global_load_ushort v47, v[36:37], off
	v_or_b32_e32 v21, s18, v69
	v_mad_i64_i32 v[24:25], s[0:1], v21, s23, v[14:15]
	v_lshl_add_u64 v[24:25], v[24:25], 0, s[16:17]
	v_lshl_add_u64 v[30:31], v[24:25], 0, v[0:1]
	v_lshl_add_u64 v[34:35], v[30:31], 0, s[10:11]
	v_lshl_add_u64 v[36:37], v[30:31], 0, s[20:21]
	global_load_ushort v40, v[30:31], off
	global_load_ushort v44, v[34:35], off
	global_load_ushort v48, v[36:37], off
	v_lshl_add_u64 v[32:33], v[24:25], 0, v[18:19]
	v_lshl_add_u64 v[34:35], v[32:33], 0, s[10:11]
	v_lshl_add_u64 v[36:37], v[32:33], 0, s[20:21]
	global_load_ushort v41, v[32:33], off
	global_load_ushort v45, v[34:35], off
	global_load_ushort v49, v[36:37], off
	s_waitcnt vmcnt(0)
	v_and_b32_e32 v54, v71, v20
	v_lshlrev_b32_e32 v55, 16, v38
	v_lshlrev_b32_e32 v56, 16, v42
	v_lshlrev_b32_e32 v57, 16, v46
	v_cmp_ne_u32_e32 vcc, 0, v54
	s_nop 1
	v_cndmask_b32_e32 v56, 0, v56, vcc
	v_cmp_ne_u32_e32 vcc, s22, v54
	s_nop 1
	v_cndmask_b32_e32 v57, 0, v57, vcc
	v_sub_f32_e32 v56, v56, v55
	v_sub_f32_e32 v57, v57, v55
	v_mul_f32_e32 v56, v56, v50
	v_mul_f32_e32 v57, v57, v51
	v_add_f32_e32 v56, v56, v55
	v_add_f32_e32 v56, v56, v57
	v_add_f32_e64 v57, |v56|, |v56|
	v_mul_f32_e32 v58, 0x3fb8aa3b, v57
	v_rndne_f32_e32 v59, v58
	v_sub_f32_e32 v60, v58, v59
	v_fma_f32 v58, v57, s35, -v58
	v_fmac_f32_e32 v58, 0x32a5705f, v57
	v_add_f32_e32 v58, v60, v58
	v_cvt_i32_f32_e32 v59, v59
	v_exp_f32_e32 v58, v58
	v_cmp_ngt_f32_e32 vcc, s44, v57
	v_ldexp_f32 v58, v58, v59
	s_nop 0
	v_cndmask_b32_e32 v58, 0, v58, vcc
	v_cmp_nlt_f32_e32 vcc, s45, v57
	s_nop 1
	v_cndmask_b32_e32 v57, v73, v58, vcc
	v_add_f32_e32 v57, 1.0, v57
	v_rcp_f32_e32 v57, v57
	s_nop 0
	v_fma_f32 v58, v57, -2.0, 1.0
	v_mul_f32_e32 v57, v56, v56
	v_fmamk_f32 v59, v57, 0xbbbac73d, v72
	v_fmaak_f32 v59, v57, v59, 0xbd5c1c4e
	v_fmaak_f32 v59, v57, v59, 0x3e088382
	v_fmaak_f32 v59, v57, v59, 0xbeaaaa99
	v_mul_f32_e64 v59, |v56|, v59
	v_fma_f32 v59, v57, v59, |v56|
	v_cmp_nlt_f32_e64 vcc, |v56|, s34
	s_nop 1
	v_cndmask_b32_e32 v58, v59, v58, vcc
	v_bfi_b32 v56, s46, v58, v56
	ds_write_b32 v68, v56
	v_and_b32_e32 v54, v71, v20
	v_lshlrev_b32_e32 v55, 16, v39
	v_lshlrev_b32_e32 v56, 16, v43
	v_lshlrev_b32_e32 v57, 16, v47
	v_cmp_ne_u32_e32 vcc, 0, v54
	s_nop 1
	v_cndmask_b32_e32 v56, 0, v56, vcc
	v_cmp_ne_u32_e32 vcc, s22, v54
	s_nop 1
	v_cndmask_b32_e32 v57, 0, v57, vcc
	v_sub_f32_e32 v56, v56, v55
	v_sub_f32_e32 v57, v57, v55
	v_mul_f32_e32 v56, v56, v52
	v_mul_f32_e32 v57, v57, v53
	v_add_f32_e32 v56, v56, v55
	v_add_f32_e32 v56, v56, v57
	ds_write_b32 v68, v56 offset:4096
	v_and_b32_e32 v54, v71, v21
	v_lshlrev_b32_e32 v55, 16, v40
	v_lshlrev_b32_e32 v56, 16, v44
	v_lshlrev_b32_e32 v57, 16, v48
	v_cmp_ne_u32_e32 vcc, 0, v54
	s_nop 1
	v_cndmask_b32_e32 v56, 0, v56, vcc
	v_cmp_ne_u32_e32 vcc, s22, v54
	s_nop 1
	v_cndmask_b32_e32 v57, 0, v57, vcc
	v_sub_f32_e32 v56, v56, v55
	v_sub_f32_e32 v57, v57, v55
	v_mul_f32_e32 v56, v56, v50
	v_mul_f32_e32 v57, v57, v51
	v_add_f32_e32 v56, v56, v55
	v_add_f32_e32 v56, v56, v57
	v_add_f32_e64 v57, |v56|, |v56|
	v_mul_f32_e32 v58, 0x3fb8aa3b, v57
	v_rndne_f32_e32 v59, v58
	v_sub_f32_e32 v60, v58, v59
	v_fma_f32 v58, v57, s35, -v58
	v_fmac_f32_e32 v58, 0x32a5705f, v57
	v_add_f32_e32 v58, v60, v58
	v_cvt_i32_f32_e32 v59, v59
	v_exp_f32_e32 v58, v58
	v_cmp_ngt_f32_e32 vcc, s44, v57
	v_ldexp_f32 v58, v58, v59
	s_nop 0
	v_cndmask_b32_e32 v58, 0, v58, vcc
	v_cmp_nlt_f32_e32 vcc, s45, v57
	s_nop 1
	v_cndmask_b32_e32 v57, v73, v58, vcc
	v_add_f32_e32 v57, 1.0, v57
	v_rcp_f32_e32 v57, v57
	s_nop 0
	v_fma_f32 v58, v57, -2.0, 1.0
	v_mul_f32_e32 v57, v56, v56
	v_fmamk_f32 v59, v57, 0xbbbac73d, v72
	v_fmaak_f32 v59, v57, v59, 0xbd5c1c4e
	v_fmaak_f32 v59, v57, v59, 0x3e088382
	v_fmaak_f32 v59, v57, v59, 0xbeaaaa99
	v_mul_f32_e64 v59, |v56|, v59
	v_fma_f32 v59, v57, v59, |v56|
	v_cmp_nlt_f32_e64 vcc, |v56|, s34
	s_nop 1
	v_cndmask_b32_e32 v58, v59, v58, vcc
	v_bfi_b32 v56, s46, v58, v56
	ds_write_b32 v70, v56
	v_and_b32_e32 v54, v71, v21
	v_lshlrev_b32_e32 v55, 16, v41
	v_lshlrev_b32_e32 v56, 16, v45
	v_lshlrev_b32_e32 v57, 16, v49
	v_cmp_ne_u32_e32 vcc, 0, v54
	s_nop 1
	v_cndmask_b32_e32 v56, 0, v56, vcc
	v_cmp_ne_u32_e32 vcc, s22, v54
	s_nop 1
	v_cndmask_b32_e32 v57, 0, v57, vcc
	v_sub_f32_e32 v56, v56, v55
	v_sub_f32_e32 v57, v57, v55
	v_mul_f32_e32 v56, v56, v52
	v_mul_f32_e32 v57, v57, v53
	v_add_f32_e32 v56, v56, v55
	v_add_f32_e32 v56, v56, v57
	ds_write_b32 v70, v56 offset:4096
	s_waitcnt lgkmcnt(0)
	s_barrier
	v_and_b32_e32 v112, 63, v164
	v_lshrrev_b32_e32 v113, 6, v164
	v_lshlrev_b32_e32 v107, 2, v112
	v_lshrrev_b32_e32 v114, 4, v112
	v_and_b32_e32 v115, 15, v112
	v_lshlrev_b32_e32 v111, 11, v114
	v_lshl_add_u32 v111, v113, 8, v111
	v_lshl_add_u32 v111, v115, 4, v111
	v_lshlrev_b32_e32 v109, 12, v114
	v_lshl_add_u32 v109, v113, 7, v109
	v_lshl_add_u32 v109, v115, 3, v109
	v_mov_b32_e32 v114, v109
	v_mov_b32_e32 v115, 0
	v_readlane_b32 s50, v255, 27
	v_readlane_b32 s51, v255, 28
	v_readlane_b32 s54, v255, 31
	v_readlane_b32 s55, v255, 32
	s_add_u32 s52, s50, 0x20000
	s_addc_u32 s53, s51, 0
	s_lshl_b32 s58, s18, 10
	v_mov_b32_e32 v108, v111
	global_load_dwordx4 v[92:95], v108, s[50:51]
	v_add_u32_e32 v108, 0x2000, v108
	ds_read_b32 v104, v107 offset:0
	global_load_dwordx4 v[96:99], v108, s[50:51]
	v_add_u32_e32 v108, 0x2000, v108
	ds_read_b32 v105, v107 offset:256
	global_load_dwordx4 v[100:103], v108, s[50:51]
	v_add_u32_e32 v108, 0x2000, v108
	ds_read_b32 v106, v107 offset:512
	s_waitcnt vmcnt(2) lgkmcnt(2)
	v_mfma_f32_16x16x4_f32 v[76:79], v104, v92, 0
	v_mfma_f32_16x16x4_f32 v[80:83], v104, v93, 0
	v_mfma_f32_16x16x4_f32 v[84:87], v104, v94, 0
	v_mfma_f32_16x16x4_f32 v[88:91], v104, v95, 0
	global_load_dwordx4 v[92:95], v108, s[50:51]
	v_add_u32_e32 v108, 0x2000, v108
	ds_read_b32 v104, v107 offset:768
	s_waitcnt vmcnt(2) lgkmcnt(2)
	v_mfma_f32_16x16x4_f32 v[76:79], v105, v96, v[76:79]
	v_mfma_f32_16x16x4_f32 v[80:83], v105, v97, v[80:83]
	v_mfma_f32_16x16x4_f32 v[84:87], v105, v98, v[84:87]
	v_mfma_f32_16x16x4_f32 v[88:91], v105, v99, v[88:91]
	global_load_dwordx4 v[96:99], v108, s[50:51]
	v_add_u32_e32 v108, 0x2000, v108
	ds_read_b32 v105, v107 offset:1024
	s_waitcnt vmcnt(2) lgkmcnt(2)
	v_mfma_f32_16x16x4_f32 v[76:79], v106, v100, v[76:79]
	v_mfma_f32_16x16x4_f32 v[80:83], v106, v101, v[80:83]
	v_mfma_f32_16x16x4_f32 v[84:87], v106, v102, v[84:87]
	v_mfma_f32_16x16x4_f32 v[88:91], v106, v103, v[88:91]
	global_load_dwordx4 v[100:103], v108, s[50:51]
	v_add_u32_e32 v108, 0x2000, v108
	ds_read_b32 v106, v107 offset:1280
	s_waitcnt vmcnt(2) lgkmcnt(2)
	v_mfma_f32_16x16x4_f32 v[76:79], v104, v92, v[76:79]
	v_mfma_f32_16x16x4_f32 v[80:83], v104, v93, v[80:83]
	v_mfma_f32_16x16x4_f32 v[84:87], v104, v94, v[84:87]
	v_mfma_f32_16x16x4_f32 v[88:91], v104, v95, v[88:91]
	global_load_dwordx4 v[92:95], v108, s[50:51]
	v_add_u32_e32 v108, 0x2000, v108
	ds_read_b32 v104, v107 offset:1536
	s_waitcnt vmcnt(2) lgkmcnt(2)
	v_mfma_f32_16x16x4_f32 v[76:79], v105, v96, v[76:79]
	v_mfma_f32_16x16x4_f32 v[80:83], v105, v97, v[80:83]
	v_mfma_f32_16x16x4_f32 v[84:87], v105, v98, v[84:87]
	v_mfma_f32_16x16x4_f32 v[88:91], v105, v99, v[88:91]
	global_load_dwordx4 v[96:99], v108, s[50:51]
	v_add_u32_e32 v108, 0x2000, v108
	ds_read_b32 v105, v107 offset:1792
	s_waitcnt vmcnt(2) lgkmcnt(2)
	v_mfma_f32_16x16x4_f32 v[76:79], v106, v100, v[76:79]
	v_mfma_f32_16x16x4_f32 v[80:83], v106, v101, v[80:83]
	v_mfma_f32_16x16x4_f32 v[84:87], v106, v102, v[84:87]
	v_mfma_f32_16x16x4_f32 v[88:91], v106, v103, v[88:91]
	global_load_dwordx4 v[100:103], v108, s[50:51]
	v_add_u32_e32 v108, 0x2000, v108
	ds_read_b32 v106, v107 offset:2048
	s_waitcnt vmcnt(2) lgkmcnt(2)
	v_mfma_f32_16x16x4_f32 v[76:79], v104, v92, v[76:79]
	v_mfma_f32_16x16x4_f32 v[80:83], v104, v93, v[80:83]
	v_mfma_f32_16x16x4_f32 v[84:87], v104, v94, v[84:87]
	v_mfma_f32_16x16x4_f32 v[88:91], v104, v95, v[88:91]
	global_load_dwordx4 v[92:95], v108, s[50:51]
	v_add_u32_e32 v108, 0x2000, v108
	ds_read_b32 v104, v107 offset:2304
	s_waitcnt vmcnt(2) lgkmcnt(2)
	v_mfma_f32_16x16x4_f32 v[76:79], v105, v96, v[76:79]
	v_mfma_f32_16x16x4_f32 v[80:83], v105, v97, v[80:83]
	v_mfma_f32_16x16x4_f32 v[84:87], v105, v98, v[84:87]
	v_mfma_f32_16x16x4_f32 v[88:91], v105, v99, v[88:91]
	global_load_dwordx4 v[96:99], v108, s[50:51]
	v_add_u32_e32 v108, 0x2000, v108
	ds_read_b32 v105, v107 offset:2560
	s_waitcnt vmcnt(2) lgkmcnt(2)
	v_mfma_f32_16x16x4_f32 v[76:79], v106, v100, v[76:79]
	v_mfma_f32_16x16x4_f32 v[80:83], v106, v101, v[80:83]
	v_mfma_f32_16x16x4_f32 v[84:87], v106, v102, v[84:87]
	v_mfma_f32_16x16x4_f32 v[88:91], v106, v103, v[88:91]
	global_load_dwordx4 v[100:103], v108, s[50:51]
	v_add_u32_e32 v108, 0x2000, v108
	ds_read_b32 v106, v107 offset:2816
	s_waitcnt vmcnt(2) lgkmcnt(2)
	v_mfma_f32_16x16x4_f32 v[76:79], v104, v92, v[76:79]
	v_mfma_f32_16x16x4_f32 v[80:83], v104, v93, v[80:83]
	v_mfma_f32_16x16x4_f32 v[84:87], v104, v94, v[84:87]
	v_mfma_f32_16x16x4_f32 v[88:91], v104, v95, v[88:91]
	global_load_dwordx4 v[92:95], v108, s[50:51]
	v_add_u32_e32 v108, 0x2000, v108
	ds_read_b32 v104, v107 offset:3072
	s_waitcnt vmcnt(2) lgkmcnt(2)
	v_mfma_f32_16x16x4_f32 v[76:79], v105, v96, v[76:79]
	v_mfma_f32_16x16x4_f32 v[80:83], v105, v97, v[80:83]
	v_mfma_f32_16x16x4_f32 v[84:87], v105, v98, v[84:87]
	v_mfma_f32_16x16x4_f32 v[88:91], v105, v99, v[88:91]
	global_load_dwordx4 v[96:99], v108, s[50:51]
	v_add_u32_e32 v108, 0x2000, v108
	ds_read_b32 v105, v107 offset:3328
	s_waitcnt vmcnt(2) lgkmcnt(2)
	v_mfma_f32_16x16x4_f32 v[76:79], v106, v100, v[76:79]
	v_mfma_f32_16x16x4_f32 v[80:83], v106, v101, v[80:83]
	v_mfma_f32_16x16x4_f32 v[84:87], v106, v102, v[84:87]
	v_mfma_f32_16x16x4_f32 v[88:91], v106, v103, v[88:91]
	global_load_dwordx4 v[100:103], v108, s[50:51]
	v_add_u32_e32 v108, 0x2000, v108
	ds_read_b32 v106, v107 offset:3584
	s_waitcnt vmcnt(2) lgkmcnt(2)
	v_mfma_f32_16x16x4_f32 v[76:79], v104, v92, v[76:79]
	v_mfma_f32_16x16x4_f32 v[80:83], v104, v93, v[80:83]
	v_mfma_f32_16x16x4_f32 v[84:87], v104, v94, v[84:87]
	v_mfma_f32_16x16x4_f32 v[88:91], v104, v95, v[88:91]
	global_load_dwordx4 v[92:95], v108, s[50:51]
	v_add_u32_e32 v108, 0x2000, v108
	ds_read_b32 v104, v107 offset:3840
	s_waitcnt vmcnt(2) lgkmcnt(2)
	v_mfma_f32_16x16x4_f32 v[76:79], v105, v96, v[76:79]
	v_mfma_f32_16x16x4_f32 v[80:83], v105, v97, v[80:83]
	v_mfma_f32_16x16x4_f32 v[84:87], v105, v98, v[84:87]
	v_mfma_f32_16x16x4_f32 v[88:91], v105, v99, v[88:91]
	v_mov_b32_e32 v108, v111
	global_load_dwordx4 v[96:99], v108, s[52:53]
	v_add_u32_e32 v108, 0x2000, v108
	ds_read_b32 v105, v107 offset:0
	s_waitcnt vmcnt(2) lgkmcnt(2)
	v_mfma_f32_16x16x4_f32 v[76:79], v106, v100, v[76:79]
	v_mfma_f32_16x16x4_f32 v[80:83], v106, v101, v[80:83]
	v_mfma_f32_16x16x4_f32 v[84:87], v106, v102, v[84:87]
	v_mfma_f32_16x16x4_f32 v[88:91], v106, v103, v[88:91]
	global_load_dwordx4 v[100:103], v108, s[52:53]
	v_add_u32_e32 v108, 0x2000, v108
	ds_read_b32 v106, v107 offset:256
	s_waitcnt vmcnt(2) lgkmcnt(2)
	v_mfma_f32_16x16x4_f32 v[76:79], v104, v92, v[76:79]
	v_mfma_f32_16x16x4_f32 v[80:83], v104, v93, v[80:83]
	v_mfma_f32_16x16x4_f32 v[84:87], v104, v94, v[84:87]
	v_mfma_f32_16x16x4_f32 v[88:91], v104, v95, v[88:91]
	s_add_u32 s56, s26, 0x2000000
	s_addc_u32 s57, s27, 0
	s_add_u32 s56, s56, s58
	s_addc_u32 s57, s57, 0
	v_lshl_add_u64 v[112:113], s[56:57], 0, v[114:115]
	s_nop 15
	s_nop 7
	v_cvt_pk_bf16_f32 v20, v76, v80
	v_cvt_pk_bf16_f32 v21, v84, v88
	global_store_dwordx2 v[112:113], v[20:21], off
	v_cvt_pk_bf16_f32 v22, v77, v81
	v_cvt_pk_bf16_f32 v23, v85, v89
	global_store_dwordx2 v[112:113], v[22:23], off offset:1024
	v_cvt_pk_bf16_f32 v24, v78, v82
	v_cvt_pk_bf16_f32 v25, v86, v90
	global_store_dwordx2 v[112:113], v[24:25], off offset:2048
	v_cvt_pk_bf16_f32 v26, v79, v83
	v_cvt_pk_bf16_f32 v27, v87, v91
	global_store_dwordx2 v[112:113], v[26:27], off offset:3072
	global_load_dwordx4 v[92:95], v108, s[52:53]
	v_add_u32_e32 v108, 0x2000, v108
	ds_read_b32 v104, v107 offset:512
	s_waitcnt vmcnt(6) lgkmcnt(2)
	v_mfma_f32_16x16x4_f32 v[76:79], v105, v96, 0
	v_mfma_f32_16x16x4_f32 v[80:83], v105, v97, 0
	v_mfma_f32_16x16x4_f32 v[84:87], v105, v98, 0
	v_mfma_f32_16x16x4_f32 v[88:91], v105, v99, 0
	global_load_dwordx4 v[96:99], v108, s[52:53]
	v_add_u32_e32 v108, 0x2000, v108
	ds_read_b32 v105, v107 offset:768
	s_waitcnt vmcnt(6) lgkmcnt(2)
	v_mfma_f32_16x16x4_f32 v[76:79], v106, v100, v[76:79]
	v_mfma_f32_16x16x4_f32 v[80:83], v106, v101, v[80:83]
	v_mfma_f32_16x16x4_f32 v[84:87], v106, v102, v[84:87]
	v_mfma_f32_16x16x4_f32 v[88:91], v106, v103, v[88:91]
	global_load_dwordx4 v[100:103], v108, s[52:53]
	v_add_u32_e32 v108, 0x2000, v108
	ds_read_b32 v106, v107 offset:1024
	s_waitcnt vmcnt(2) lgkmcnt(2)
	v_mfma_f32_16x16x4_f32 v[76:79], v104, v92, v[76:79]
	v_mfma_f32_16x16x4_f32 v[80:83], v104, v93, v[80:83]
	v_mfma_f32_16x16x4_f32 v[84:87], v104, v94, v[84:87]
	v_mfma_f32_16x16x4_f32 v[88:91], v104, v95, v[88:91]
	global_load_dwordx4 v[92:95], v108, s[52:53]
	v_add_u32_e32 v108, 0x2000, v108
	ds_read_b32 v104, v107 offset:1280
	s_waitcnt vmcnt(2) lgkmcnt(2)
	v_mfma_f32_16x16x4_f32 v[76:79], v105, v96, v[76:79]
	v_mfma_f32_16x16x4_f32 v[80:83], v105, v97, v[80:83]
	v_mfma_f32_16x16x4_f32 v[84:87], v105, v98, v[84:87]
	v_mfma_f32_16x16x4_f32 v[88:91], v105, v99, v[88:91]
	global_load_dwordx4 v[96:99], v108, s[52:53]
	v_add_u32_e32 v108, 0x2000, v108
	ds_read_b32 v105, v107 offset:1536
	s_waitcnt vmcnt(2) lgkmcnt(2)
	v_mfma_f32_16x16x4_f32 v[76:79], v106, v100, v[76:79]
	v_mfma_f32_16x16x4_f32 v[80:83], v106, v101, v[80:83]
	v_mfma_f32_16x16x4_f32 v[84:87], v106, v102, v[84:87]
	v_mfma_f32_16x16x4_f32 v[88:91], v106, v103, v[88:91]
	global_load_dwordx4 v[100:103], v108, s[52:53]
	v_add_u32_e32 v108, 0x2000, v108
	ds_read_b32 v106, v107 offset:1792
	s_waitcnt vmcnt(2) lgkmcnt(2)
	v_mfma_f32_16x16x4_f32 v[76:79], v104, v92, v[76:79]
	v_mfma_f32_16x16x4_f32 v[80:83], v104, v93, v[80:83]
	v_mfma_f32_16x16x4_f32 v[84:87], v104, v94, v[84:87]
	v_mfma_f32_16x16x4_f32 v[88:91], v104, v95, v[88:91]
	global_load_dwordx4 v[92:95], v108, s[52:53]
	v_add_u32_e32 v108, 0x2000, v108
	ds_read_b32 v104, v107 offset:2048
	s_waitcnt vmcnt(2) lgkmcnt(2)
	v_mfma_f32_16x16x4_f32 v[76:79], v105, v96, v[76:79]
	v_mfma_f32_16x16x4_f32 v[80:83], v105, v97, v[80:83]
	v_mfma_f32_16x16x4_f32 v[84:87], v105, v98, v[84:87]
	v_mfma_f32_16x16x4_f32 v[88:91], v105, v99, v[88:91]
	global_load_dwordx4 v[96:99], v108, s[52:53]
	v_add_u32_e32 v108, 0x2000, v108
	ds_read_b32 v105, v107 offset:2304
	s_waitcnt vmcnt(2) lgkmcnt(2)
	v_mfma_f32_16x16x4_f32 v[76:79], v106, v100, v[76:79]
	v_mfma_f32_16x16x4_f32 v[80:83], v106, v101, v[80:83]
	v_mfma_f32_16x16x4_f32 v[84:87], v106, v102, v[84:87]
	v_mfma_f32_16x16x4_f32 v[88:91], v106, v103, v[88:91]
	global_load_dwordx4 v[100:103], v108, s[52:53]
	v_add_u32_e32 v108, 0x2000, v108
	ds_read_b32 v106, v107 offset:2560
	s_waitcnt vmcnt(2) lgkmcnt(2)
	v_mfma_f32_16x16x4_f32 v[76:79], v104, v92, v[76:79]
	v_mfma_f32_16x16x4_f32 v[80:83], v104, v93, v[80:83]
	v_mfma_f32_16x16x4_f32 v[84:87], v104, v94, v[84:87]
	v_mfma_f32_16x16x4_f32 v[88:91], v104, v95, v[88:91]
	global_load_dwordx4 v[92:95], v108, s[52:53]
	v_add_u32_e32 v108, 0x2000, v108
	ds_read_b32 v104, v107 offset:2816
	s_waitcnt vmcnt(2) lgkmcnt(2)
	v_mfma_f32_16x16x4_f32 v[76:79], v105, v96, v[76:79]
	v_mfma_f32_16x16x4_f32 v[80:83], v105, v97, v[80:83]
	v_mfma_f32_16x16x4_f32 v[84:87], v105, v98, v[84:87]
	v_mfma_f32_16x16x4_f32 v[88:91], v105, v99, v[88:91]
	global_load_dwordx4 v[96:99], v108, s[52:53]
	v_add_u32_e32 v108, 0x2000, v108
	ds_read_b32 v105, v107 offset:3072
	s_waitcnt vmcnt(2) lgkmcnt(2)
	v_mfma_f32_16x16x4_f32 v[76:79], v106, v100, v[76:79]
	v_mfma_f32_16x16x4_f32 v[80:83], v106, v101, v[80:83]
	v_mfma_f32_16x16x4_f32 v[84:87], v106, v102, v[84:87]
	v_mfma_f32_16x16x4_f32 v[88:91], v106, v103, v[88:91]
	global_load_dwordx4 v[100:103], v108, s[52:53]
	v_add_u32_e32 v108, 0x2000, v108
	ds_read_b32 v106, v107 offset:3328
	s_waitcnt vmcnt(2) lgkmcnt(2)
	v_mfma_f32_16x16x4_f32 v[76:79], v104, v92, v[76:79]
	v_mfma_f32_16x16x4_f32 v[80:83], v104, v93, v[80:83]
	v_mfma_f32_16x16x4_f32 v[84:87], v104, v94, v[84:87]
	v_mfma_f32_16x16x4_f32 v[88:91], v104, v95, v[88:91]
	global_load_dwordx4 v[92:95], v108, s[52:53]
	v_add_u32_e32 v108, 0x2000, v108
	ds_read_b32 v104, v107 offset:3584
	s_waitcnt vmcnt(2) lgkmcnt(2)
	v_mfma_f32_16x16x4_f32 v[76:79], v105, v96, v[76:79]
	v_mfma_f32_16x16x4_f32 v[80:83], v105, v97, v[80:83]
	v_mfma_f32_16x16x4_f32 v[84:87], v105, v98, v[84:87]
	v_mfma_f32_16x16x4_f32 v[88:91], v105, v99, v[88:91]
	global_load_dwordx4 v[96:99], v108, s[52:53]
	v_add_u32_e32 v108, 0x2000, v108
	ds_read_b32 v105, v107 offset:3840
	s_waitcnt vmcnt(2) lgkmcnt(2)
	v_mfma_f32_16x16x4_f32 v[76:79], v106, v100, v[76:79]
	v_mfma_f32_16x16x4_f32 v[80:83], v106, v101, v[80:83]
	v_mfma_f32_16x16x4_f32 v[84:87], v106, v102, v[84:87]
	v_mfma_f32_16x16x4_f32 v[88:91], v106, v103, v[88:91]
	v_mov_b32_e32 v108, v111
	global_load_dwordx4 v[100:103], v108, s[54:55]
	v_add_u32_e32 v108, 0x2000, v108
	ds_read_b32 v106, v107 offset:4096
	s_waitcnt vmcnt(2) lgkmcnt(2)
	v_mfma_f32_16x16x4_f32 v[76:79], v104, v92, v[76:79]
	v_mfma_f32_16x16x4_f32 v[80:83], v104, v93, v[80:83]
	v_mfma_f32_16x16x4_f32 v[84:87], v104, v94, v[84:87]
	v_mfma_f32_16x16x4_f32 v[88:91], v104, v95, v[88:91]
	global_load_dwordx4 v[92:95], v108, s[54:55]
	v_add_u32_e32 v108, 0x2000, v108
	ds_read_b32 v104, v107 offset:4352
	s_waitcnt vmcnt(2) lgkmcnt(2)
	v_mfma_f32_16x16x4_f32 v[76:79], v105, v96, v[76:79]
	v_mfma_f32_16x16x4_f32 v[80:83], v105, v97, v[80:83]
	v_mfma_f32_16x16x4_f32 v[84:87], v105, v98, v[84:87]
	v_mfma_f32_16x16x4_f32 v[88:91], v105, v99, v[88:91]
	s_add_u32 s56, s26, 0x3000000
	s_addc_u32 s57, s27, 0
	s_add_u32 s56, s56, s58
	s_addc_u32 s57, s57, 0
	v_lshl_add_u64 v[112:113], s[56:57], 0, v[114:115]
	s_nop 15
	s_nop 7
	v_cvt_pk_bf16_f32 v20, v76, v80
	v_cvt_pk_bf16_f32 v21, v84, v88
	global_store_dwordx2 v[112:113], v[20:21], off
	v_cvt_pk_bf16_f32 v22, v77, v81
	v_cvt_pk_bf16_f32 v23, v85, v89
	global_store_dwordx2 v[112:113], v[22:23], off offset:1024
	v_cvt_pk_bf16_f32 v24, v78, v82
	v_cvt_pk_bf16_f32 v25, v86, v90
	global_store_dwordx2 v[112:113], v[24:25], off offset:2048
	v_cvt_pk_bf16_f32 v26, v79, v83
	v_cvt_pk_bf16_f32 v27, v87, v91
	global_store_dwordx2 v[112:113], v[26:27], off offset:3072
	global_load_dwordx4 v[96:99], v108, s[54:55]
	v_add_u32_e32 v108, 0x2000, v108
	ds_read_b32 v105, v107 offset:4608
	s_waitcnt vmcnt(6) lgkmcnt(2)
	v_mfma_f32_16x16x4_f32 v[76:79], v106, v100, 0
	v_mfma_f32_16x16x4_f32 v[80:83], v106, v101, 0
	v_mfma_f32_16x16x4_f32 v[84:87], v106, v102, 0
	v_mfma_f32_16x16x4_f32 v[88:91], v106, v103, 0
	global_load_dwordx4 v[100:103], v108, s[54:55]
	v_add_u32_e32 v108, 0x2000, v108
	ds_read_b32 v106, v107 offset:4864
	s_waitcnt vmcnt(6) lgkmcnt(2)
	v_mfma_f32_16x16x4_f32 v[76:79], v104, v92, v[76:79]
	v_mfma_f32_16x16x4_f32 v[80:83], v104, v93, v[80:83]
	v_mfma_f32_16x16x4_f32 v[84:87], v104, v94, v[84:87]
	v_mfma_f32_16x16x4_f32 v[88:91], v104, v95, v[88:91]
	global_load_dwordx4 v[92:95], v108, s[54:55]
	v_add_u32_e32 v108, 0x2000, v108
	ds_read_b32 v104, v107 offset:5120
	s_waitcnt vmcnt(2) lgkmcnt(2)
	v_mfma_f32_16x16x4_f32 v[76:79], v105, v96, v[76:79]
	v_mfma_f32_16x16x4_f32 v[80:83], v105, v97, v[80:83]
	v_mfma_f32_16x16x4_f32 v[84:87], v105, v98, v[84:87]
	v_mfma_f32_16x16x4_f32 v[88:91], v105, v99, v[88:91]
	global_load_dwordx4 v[96:99], v108, s[54:55]
	v_add_u32_e32 v108, 0x2000, v108
	ds_read_b32 v105, v107 offset:5376
	s_waitcnt vmcnt(2) lgkmcnt(2)
	v_mfma_f32_16x16x4_f32 v[76:79], v106, v100, v[76:79]
	v_mfma_f32_16x16x4_f32 v[80:83], v106, v101, v[80:83]
	v_mfma_f32_16x16x4_f32 v[84:87], v106, v102, v[84:87]
	v_mfma_f32_16x16x4_f32 v[88:91], v106, v103, v[88:91]
	global_load_dwordx4 v[100:103], v108, s[54:55]
	v_add_u32_e32 v108, 0x2000, v108
	ds_read_b32 v106, v107 offset:5632
	s_waitcnt vmcnt(2) lgkmcnt(2)
	v_mfma_f32_16x16x4_f32 v[76:79], v104, v92, v[76:79]
	v_mfma_f32_16x16x4_f32 v[80:83], v104, v93, v[80:83]
	v_mfma_f32_16x16x4_f32 v[84:87], v104, v94, v[84:87]
	v_mfma_f32_16x16x4_f32 v[88:91], v104, v95, v[88:91]
	global_load_dwordx4 v[92:95], v108, s[54:55]
	v_add_u32_e32 v108, 0x2000, v108
	ds_read_b32 v104, v107 offset:5888
	s_waitcnt vmcnt(2) lgkmcnt(2)
	v_mfma_f32_16x16x4_f32 v[76:79], v105, v96, v[76:79]
	v_mfma_f32_16x16x4_f32 v[80:83], v105, v97, v[80:83]
	v_mfma_f32_16x16x4_f32 v[84:87], v105, v98, v[84:87]
	v_mfma_f32_16x16x4_f32 v[88:91], v105, v99, v[88:91]
	global_load_dwordx4 v[96:99], v108, s[54:55]
	v_add_u32_e32 v108, 0x2000, v108
	ds_read_b32 v105, v107 offset:6144
	s_waitcnt vmcnt(2) lgkmcnt(2)
	v_mfma_f32_16x16x4_f32 v[76:79], v106, v100, v[76:79]
	v_mfma_f32_16x16x4_f32 v[80:83], v106, v101, v[80:83]
	v_mfma_f32_16x16x4_f32 v[84:87], v106, v102, v[84:87]
	v_mfma_f32_16x16x4_f32 v[88:91], v106, v103, v[88:91]
	global_load_dwordx4 v[100:103], v108, s[54:55]
	v_add_u32_e32 v108, 0x2000, v108
	ds_read_b32 v106, v107 offset:6400
	s_waitcnt vmcnt(2) lgkmcnt(2)
	v_mfma_f32_16x16x4_f32 v[76:79], v104, v92, v[76:79]
	v_mfma_f32_16x16x4_f32 v[80:83], v104, v93, v[80:83]
	v_mfma_f32_16x16x4_f32 v[84:87], v104, v94, v[84:87]
	v_mfma_f32_16x16x4_f32 v[88:91], v104, v95, v[88:91]
	global_load_dwordx4 v[92:95], v108, s[54:55]
	v_add_u32_e32 v108, 0x2000, v108
	ds_read_b32 v104, v107 offset:6656
	s_waitcnt vmcnt(2) lgkmcnt(2)
	v_mfma_f32_16x16x4_f32 v[76:79], v105, v96, v[76:79]
	v_mfma_f32_16x16x4_f32 v[80:83], v105, v97, v[80:83]
	v_mfma_f32_16x16x4_f32 v[84:87], v105, v98, v[84:87]
	v_mfma_f32_16x16x4_f32 v[88:91], v105, v99, v[88:91]
	global_load_dwordx4 v[96:99], v108, s[54:55]
	v_add_u32_e32 v108, 0x2000, v108
	ds_read_b32 v105, v107 offset:6912
	s_waitcnt vmcnt(2) lgkmcnt(2)
	v_mfma_f32_16x16x4_f32 v[76:79], v106, v100, v[76:79]
	v_mfma_f32_16x16x4_f32 v[80:83], v106, v101, v[80:83]
	v_mfma_f32_16x16x4_f32 v[84:87], v106, v102, v[84:87]
	v_mfma_f32_16x16x4_f32 v[88:91], v106, v103, v[88:91]
	global_load_dwordx4 v[100:103], v108, s[54:55]
	v_add_u32_e32 v108, 0x2000, v108
	ds_read_b32 v106, v107 offset:7168
	s_waitcnt vmcnt(2) lgkmcnt(2)
	v_mfma_f32_16x16x4_f32 v[76:79], v104, v92, v[76:79]
	v_mfma_f32_16x16x4_f32 v[80:83], v104, v93, v[80:83]
	v_mfma_f32_16x16x4_f32 v[84:87], v104, v94, v[84:87]
	v_mfma_f32_16x16x4_f32 v[88:91], v104, v95, v[88:91]
	global_load_dwordx4 v[92:95], v108, s[54:55]
	v_add_u32_e32 v108, 0x2000, v108
	ds_read_b32 v104, v107 offset:7424
	s_waitcnt vmcnt(2) lgkmcnt(2)
	v_mfma_f32_16x16x4_f32 v[76:79], v105, v96, v[76:79]
	v_mfma_f32_16x16x4_f32 v[80:83], v105, v97, v[80:83]
	v_mfma_f32_16x16x4_f32 v[84:87], v105, v98, v[84:87]
	v_mfma_f32_16x16x4_f32 v[88:91], v105, v99, v[88:91]
	global_load_dwordx4 v[96:99], v108, s[54:55]
	v_add_u32_e32 v108, 0x2000, v108
	ds_read_b32 v105, v107 offset:7680
	s_waitcnt vmcnt(2) lgkmcnt(2)
	v_mfma_f32_16x16x4_f32 v[76:79], v106, v100, v[76:79]
	v_mfma_f32_16x16x4_f32 v[80:83], v106, v101, v[80:83]
	v_mfma_f32_16x16x4_f32 v[84:87], v106, v102, v[84:87]
	v_mfma_f32_16x16x4_f32 v[88:91], v106, v103, v[88:91]
	global_load_dwordx4 v[100:103], v108, s[54:55]
	v_add_u32_e32 v108, 0x2000, v108
	ds_read_b32 v106, v107 offset:7936
	s_waitcnt vmcnt(2) lgkmcnt(2)
	v_mfma_f32_16x16x4_f32 v[76:79], v104, v92, v[76:79]
	v_mfma_f32_16x16x4_f32 v[80:83], v104, v93, v[80:83]
	v_mfma_f32_16x16x4_f32 v[84:87], v104, v94, v[84:87]
	v_mfma_f32_16x16x4_f32 v[88:91], v104, v95, v[88:91]
	s_waitcnt vmcnt(1) lgkmcnt(1)
	v_mfma_f32_16x16x4_f32 v[76:79], v105, v96, v[76:79]
	v_mfma_f32_16x16x4_f32 v[80:83], v105, v97, v[80:83]
	v_mfma_f32_16x16x4_f32 v[84:87], v105, v98, v[84:87]
	v_mfma_f32_16x16x4_f32 v[88:91], v105, v99, v[88:91]
	s_waitcnt vmcnt(0) lgkmcnt(0)
	v_mfma_f32_16x16x4_f32 v[76:79], v106, v100, v[76:79]
	v_mfma_f32_16x16x4_f32 v[80:83], v106, v101, v[80:83]
	v_mfma_f32_16x16x4_f32 v[84:87], v106, v102, v[84:87]
	v_mfma_f32_16x16x4_f32 v[88:91], v106, v103, v[88:91]
	s_add_u32 s56, s28, 0x1a80000
	s_addc_u32 s57, s29, 0
	s_add_u32 s56, s56, s58
	s_addc_u32 s57, s57, 0
	v_lshl_add_u64 v[112:113], s[56:57], 0, v[114:115]
	s_nop 15
	s_nop 7
	v_cvt_pk_bf16_f32 v20, v76, v80
	v_cvt_pk_bf16_f32 v21, v84, v88
	global_store_dwordx2 v[112:113], v[20:21], off
	v_cvt_pk_bf16_f32 v22, v77, v81
	v_cvt_pk_bf16_f32 v23, v85, v89
	global_store_dwordx2 v[112:113], v[22:23], off offset:1024
	v_cvt_pk_bf16_f32 v24, v78, v82
	v_cvt_pk_bf16_f32 v25, v86, v90
	global_store_dwordx2 v[112:113], v[24:25], off offset:2048
	v_cvt_pk_bf16_f32 v26, v79, v83
	v_cvt_pk_bf16_f32 v27, v87, v91
	global_store_dwordx2 v[112:113], v[26:27], off offset:3072
	s_add_i32 s48, s48, s30
	s_cmpk_gt_i32 s48, 0x3ff
	s_barrier
	s_cbranch_scc0 .LBB0_944
